# residual epilogue: xb loads software-pipelined one loop iteration ahead with counted vmcnt (no store drain); 16-lane row sumsq butterfly via DPP instead of ds_bpermute
# speedup vs baseline: 1.0339x; 1.0339x over previous
; DI void epi_res(f32x16 (&acc)[4][2], int m0, int n0, const float* xold, const Params& p, char* lds) {
;     ...
;   const int c4 = (lane & 15) * 4, gcol = n0 + wc * 64 + c4;
; #pragma unroll
;   for (int pass = 0; pass < 2; ++pass) {
; #pragma unroll
;     for (int mtl = 0; mtl < 2; ++mtl)
; #pragma unroll
;       for (int nt = 0; nt < 2; ++nt)
; #pragma unroll
;         for (int g = 0; g < 4; ++g) {
;           f32x4 v; v.x = acc[pass * 2 + mtl][nt][4 * g]; v.y = acc[pass * 2 + mtl][nt][4 * g + 1]; v.z = acc[pass * 2 + mtl][nt][4 * g + 2]; v.w = acc[pass * 2 + mtl][nt][4 * g + 3];
;           *(f32x4*)(sf + (mtl * 32 + r) * 68 + nt * 32 + 8 * g + 4 * h) = v;
;         }
; #pragma unroll 4
;     for (int it = 0; it < 16; ++it) {
;       const int row_l = it * 4 + (lane >> 4);
;       const size_t grow = (size_t)(m0 + wr * 128 + pass * 64 + row_l);
;       const f32x4 a = *(const f32x4*)(sf + row_l * 68 + c4);
;       const u32x2 xw = *(const u32x2*)(p.xb + grow * 1024 + gcol);
.LBB0_263:
	v_mov_b32_e32 v0, v227
	s_movk_i32 s0, 0x4800
	s_waitcnt vmcnt(3)
	v_lshrrev_b32_e32 v130, 6, v0
	v_mul_lo_u32 v140, v130, s0
	v_and_b32_e32 v130, 0xc0, v0
	v_or_b32_e32 v134, s46, v130
	v_lshrrev_b32_e32 v130, 1, v0
	v_and_b32_e32 v135, 31, v0
	v_and_b32_e32 v141, 15, v0
	v_and_or_b32 v133, v130, 16, v140
	s_waitcnt vmcnt(2)
	v_bfe_u32 v142, v0, 4, 2
	v_ashrrev_i32_e32 v0, 1, v0
	v_and_b32_e32 v130, 64, v239
	v_and_b32_e32 v143, 0xffffff80, v0
	v_xor_b32_e32 v0, 1, v239
	v_add_u32_e32 v132, 64, v130
	v_cmp_lt_i32_e32 vcc, v0, v132
	v_xor_b32_e32 v130, 2, v239
	v_xor_b32_e32 v131, 4, v239
	v_cndmask_b32_e32 v0, v239, v0, vcc
	v_cmp_lt_i32_e32 vcc, v130, v132
	v_xor_b32_e32 v138, 8, v239
	s_movk_i32 s5, 0x110
	v_cndmask_b32_e32 v130, v239, v130, vcc
	v_cmp_lt_i32_e32 vcc, v131, v132
	v_lshl_or_b32 v136, v141, 2, v134
	s_lshl_b32 s3, s48, 8
	v_cndmask_b32_e32 v131, v239, v131, vcc
	v_cmp_lt_i32_e32 vcc, v138, v132
	v_readlane_b32 s8, v253, 36
	v_ashrrev_i32_e32 v137, 31, v136
	v_cndmask_b32_e32 v132, v239, v138, vcc
	v_ashrrev_i32_e32 v138, 6, v134
	v_mul_u32_u24_e32 v134, 0x110, v135
	v_mad_u32_u24 v135, v135, s5, v133
	ds_write_b128 v135, v[114:117]
	ds_write_b128 v135, v[118:121] offset:32
	ds_write_b128 v135, v[122:125] offset:64
	ds_write_b128 v135, v[126:129] offset:96
	ds_write_b128 v135, v[98:101] offset:128
	ds_write_b128 v135, v[102:105] offset:160
	ds_write_b128 v135, v[106:109] offset:192
	ds_write_b128 v135, v[110:113] offset:224
	ds_write_b128 v135, v[82:85] offset:8704
	ds_write_b128 v135, v[86:89] offset:8736
	ds_write_b128 v135, v[90:93] offset:8768
	ds_write_b128 v135, v[94:97] offset:8800
	ds_write_b128 v135, v[66:69] offset:8832
	ds_write_b128 v135, v[70:73] offset:8864
	ds_write_b128 v135, v[74:77] offset:8896
	ds_write_b128 v135, v[78:81] offset:8928
	v_add3_u32 v81, s2, v143, v142
	s_lshl_b32 s2, s36, 14
	s_lshl_b32 s5, s37, 11
	v_mul_u32_u24_e32 v66, 0x110, v142
	s_add_i32 s2, s2, s5
	v_or_b32_e32 v66, v140, v66
	s_or_b32 s2, s2, s3
	v_ashrrev_i32_e32 v139, 31, v138
	v_readlane_b32 s10, v253, 38
	v_readlane_b32 s11, v253, 39
	v_readlane_b32 s16, v253, 44
	v_readlane_b32 s17, v253, 45
	v_lshl_add_u32 v80, v141, 4, v66
	v_add_u32_e32 v66, s2, v143
	s_mov_b32 s4, 0
	v_lshlrev_b32_e32 v0, 2, v0
	v_lshlrev_b32_e32 v130, 2, v130
	v_lshlrev_b32_e32 v131, 2, v131
	v_lshlrev_b32_e32 v132, 2, v132
	v_cmp_eq_u32_e64 s[0:1], 0, v141
	v_lshl_add_u64 v[70:71], v[136:137], 1, s[16:17]
	v_lshl_add_u64 v[72:73], v[136:137], 2, s[10:11]
	v_lshl_add_u64 v[74:75], v[138:139], 2, s[70:71]
	v_or_b32_e32 v82, v66, v142
	v_mov_b32_e32 v83, v80
	v_readlane_b32 s9, v253, 37
	v_readlane_b32 s12, v253, 40
	v_readlane_b32 s13, v253, 41
	v_readlane_b32 s14, v253, 42
	v_readlane_b32 s15, v253, 43
	v_readlane_b32 s18, v253, 46
	v_readlane_b32 s19, v253, 47
	v_readlane_b32 s20, v253, 48
	v_readlane_b32 s21, v253, 49
	v_readlane_b32 s22, v253, 50
	v_readlane_b32 s23, v253, 51
	v_add_u32_e32 v76, 0, v82
	v_ashrrev_i32_e32 v77, 31, v76
	v_lshlrev_b64 v[78:79], 11, v[76:77]
	v_lshl_add_u64 v[78:79], v[70:71], 0, v[78:79]
	global_load_dwordx2 v[244:245], v[78:79], off
	v_add_u32_e32 v84, 0, v81
	v_add_u32_e32 v76, 4, v84
	v_ashrrev_i32_e32 v77, 31, v76
	v_lshlrev_b64 v[78:79], 11, v[76:77]
	v_lshl_add_u64 v[78:79], v[70:71], 0, v[78:79]
	global_load_dwordx2 v[246:247], v[78:79], off
	v_add_u32_e32 v76, 8, v84
	v_ashrrev_i32_e32 v77, 31, v76
	v_lshlrev_b64 v[78:79], 11, v[76:77]
	v_lshl_add_u64 v[78:79], v[70:71], 0, v[78:79]
	global_load_dwordx2 v[240:241], v[78:79], off
	v_add_u32_e32 v76, 12, v84
	v_ashrrev_i32_e32 v77, 31, v76
	v_lshlrev_b64 v[78:79], 11, v[76:77]
	v_lshl_add_u64 v[78:79], v[70:71], 0, v[78:79]
	global_load_dwordx2 v[236:237], v[78:79], off
	s_waitcnt vmcnt(0)
	s_branch .LBB0_265

; DI unsigned pk2(float a, float b) { f2_t v = {a, b}; return __builtin_bit_cast(unsigned, __builtin_convertvector(v, bf2_t)); }
; DI float bflo(unsigned w) { return __uint_as_float(w << 16); }
; DI float bfhi(unsigned w) { return __uint_as_float(w & 0xffff0000u); }
; DI void epi_res(f32x16 (&acc)[4][2], int m0, int n0, const float* xold, const Params& p, char* lds) {
;     ...
;     for (int it = 0; it < 16; ++it) {
;       const int row_l = it * 4 + (lane >> 4);
;       const size_t grow = (size_t)(m0 + wr * 128 + pass * 64 + row_l);
;       const f32x4 a = *(const f32x4*)(sf + row_l * 68 + c4);
;       const u32x2 xw = *(const u32x2*)(p.xb + grow * 1024 + gcol);
;       f32x4 v; v.x = bflo(xw.x) + a.x; v.y = bfhi(xw.x) + a.y; v.z = bflo(xw.y) + a.z; v.w = bfhi(xw.y) + a.w;
;       if (xold) *(f32x4*)(p.out + grow * 1024 + gcol) = v;
;       u32x2 w; w.x = pk2(v.x, v.y); w.y = pk2(v.z, v.w); *(u32x2*)(p.xb + grow * 1024 + gcol) = w;
;       float sq = v.x * v.x + v.y * v.y + v.z * v.z + v.w * v.w;
;       sq += __shfl_xor(sq, 1); sq += __shfl_xor(sq, 2); sq += __shfl_xor(sq, 4); sq += __shfl_xor(sq, 8);
;       if ((lane & 15) == 0) p.ssp[grow * 16 + ((n0 + wc * 64) >> 6)] = sq;
;     }
.LBB0_265:
	s_cmp_eq_u32 s4, 48
	s_cselect_b32 s96, 0, 0x8000
	s_mov_b32 s97, 0
	v_add_u32_e32 v76, s4, v82
	v_ashrrev_i32_e32 v77, 31, v76
	v_lshlrev_b64 v[78:79], 11, v[76:77]
	v_lshl_add_u64 v[78:79], v[70:71], 0, v[78:79]
	s_waitcnt vmcnt(11)
	v_mov_b32_e32 v84, v244
	v_mov_b32_e32 v85, v245
	v_lshl_add_u64 v[232:233], v[78:79], 0, s[96:97]
	global_load_dwordx2 v[244:245], v[232:233], off
	s_waitcnt lgkmcnt(0)
	ds_read_b128 v[66:69], v83
	s_andn2_b64 vcc, exec, s[44:45]
	v_lshlrev_b32_e32 v86, 16, v84
	v_and_b32_e32 v87, 0xffff0000, v84
	v_lshlrev_b32_e32 v84, 16, v85
	v_and_b32_e32 v85, 0xffff0000, v85
	s_waitcnt lgkmcnt(0)
	v_pk_add_f32 v[68:69], v[68:69], v[84:85]
	v_cndmask_b32_e64 v84, 0, 1, s[44:45]
	v_pk_add_f32 v[66:67], v[66:67], v[86:87]
	v_cmp_ne_u32_e64 s[36:37], 1, v84
	s_cbranch_vccnz .LBB0_267
	v_lshlrev_b64 v[84:85], 10, v[76:77]
	v_lshl_add_u64 v[84:85], v[84:85], 2, v[72:73]
	global_store_dwordx4 v[84:85], v[66:69], off
.LBB0_267:
	v_cvt_pk_bf16_f32 v84, v66, v67
	s_nop 0
	v_pk_mul_f32 v[66:67], v[66:67], v[66:67]
	v_cvt_pk_bf16_f32 v85, v68, v69
	v_pk_mul_f32 v[68:69], v[68:69], v[68:69]
	v_add_f32_e32 v66, v66, v67
	v_add_f32_e32 v66, v68, v66
	v_add_f32_e32 v66, v69, v66
	s_nop 1
	v_add_f32_dpp v66, v66, v66 quad_perm:[1,0,3,2] row_mask:0xf bank_mask:0xf
	global_store_dwordx2 v[78:79], v[84:85], off
	s_waitcnt lgkmcnt(0)
	s_nop 1
	v_add_f32_dpp v66, v66, v66 quad_perm:[2,3,0,1] row_mask:0xf bank_mask:0xf
	s_waitcnt lgkmcnt(0)
	s_nop 1
	v_add_f32_dpp v66, v66, v66 row_half_mirror row_mask:0xf bank_mask:0xf
	s_waitcnt lgkmcnt(0)
	s_nop 1
	v_add_f32_dpp v66, v66, v66 row_mirror row_mask:0xf bank_mask:0xf
	s_and_saveexec_b64 s[2:3], s[0:1]
	s_cbranch_execz .LBB0_269
	v_lshlrev_b64 v[68:69], 6, v[76:77]
	v_lshl_add_u64 v[68:69], v[74:75], 0, v[68:69]
	s_waitcnt lgkmcnt(0)
	global_store_dword v[68:69], v66, off
.LBB0_269:
	s_or_b64 exec, exec, s[2:3]
	v_add_u32_e32 v84, s4, v81
	v_add_u32_e32 v76, 4, v84
	v_ashrrev_i32_e32 v77, 31, v76
	v_lshlrev_b64 v[78:79], 11, v[76:77]
	v_lshl_add_u64 v[78:79], v[70:71], 0, v[78:79]
	s_waitcnt vmcnt(11)
	v_mov_b32_e32 v86, v246
	v_mov_b32_e32 v87, v247
	v_lshl_add_u64 v[232:233], v[78:79], 0, s[96:97]
	global_load_dwordx2 v[246:247], v[232:233], off
	s_waitcnt lgkmcnt(0)
	ds_read_b128 v[66:69], v83 offset:1088
	s_and_b64 vcc, exec, s[36:37]
	v_lshlrev_b32_e32 v88, 16, v86
	v_and_b32_e32 v89, 0xffff0000, v86
	v_lshlrev_b32_e32 v86, 16, v87
	v_and_b32_e32 v87, 0xffff0000, v87
	s_waitcnt lgkmcnt(0)
	v_pk_add_f32 v[66:67], v[66:67], v[88:89]
	v_pk_add_f32 v[68:69], v[68:69], v[86:87]
	s_cbranch_vccnz .LBB0_271
	v_lshlrev_b64 v[86:87], 10, v[76:77]
	v_lshl_add_u64 v[86:87], v[86:87], 2, v[72:73]
	global_store_dwordx4 v[86:87], v[66:69], off
.LBB0_271:
	v_cvt_pk_bf16_f32 v86, v66, v67
	s_nop 0
	v_pk_mul_f32 v[66:67], v[66:67], v[66:67]
	v_cvt_pk_bf16_f32 v87, v68, v69
	v_pk_mul_f32 v[68:69], v[68:69], v[68:69]
	v_add_f32_e32 v66, v66, v67
	v_add_f32_e32 v66, v68, v66
	v_add_f32_e32 v66, v69, v66
	s_nop 1
	v_add_f32_dpp v66, v66, v66 quad_perm:[1,0,3,2] row_mask:0xf bank_mask:0xf
	global_store_dwordx2 v[78:79], v[86:87], off
	s_waitcnt lgkmcnt(0)
	s_nop 1
	v_add_f32_dpp v66, v66, v66 quad_perm:[2,3,0,1] row_mask:0xf bank_mask:0xf
	s_waitcnt lgkmcnt(0)
	s_nop 1
	v_add_f32_dpp v66, v66, v66 row_half_mirror row_mask:0xf bank_mask:0xf
	s_waitcnt lgkmcnt(0)
	s_nop 1
	v_add_f32_dpp v66, v66, v66 row_mirror row_mask:0xf bank_mask:0xf
	s_and_saveexec_b64 s[2:3], s[0:1]
	s_cbranch_execz .LBB0_273
	v_lshlrev_b64 v[68:69], 6, v[76:77]
	v_lshl_add_u64 v[68:69], v[74:75], 0, v[68:69]
	s_waitcnt lgkmcnt(0)
	global_store_dword v[68:69], v66, off
.LBB0_273:
	s_or_b64 exec, exec, s[2:3]
	v_add_u32_e32 v76, 8, v84
	v_ashrrev_i32_e32 v77, 31, v76
	v_lshlrev_b64 v[78:79], 11, v[76:77]
	v_lshl_add_u64 v[78:79], v[70:71], 0, v[78:79]
	s_waitcnt vmcnt(11)
	v_mov_b32_e32 v86, v240
	v_mov_b32_e32 v87, v241
	v_lshl_add_u64 v[232:233], v[78:79], 0, s[96:97]
	global_load_dwordx2 v[240:241], v[232:233], off
	s_waitcnt lgkmcnt(0)
	ds_read_b128 v[66:69], v83 offset:2176
	s_and_b64 vcc, exec, s[36:37]
	v_lshlrev_b32_e32 v88, 16, v86
	v_and_b32_e32 v89, 0xffff0000, v86
	v_lshlrev_b32_e32 v86, 16, v87
	v_and_b32_e32 v87, 0xffff0000, v87
	s_waitcnt lgkmcnt(0)
	v_pk_add_f32 v[66:67], v[66:67], v[88:89]
	v_pk_add_f32 v[68:69], v[68:69], v[86:87]
	s_cbranch_vccnz .LBB0_275
	v_lshlrev_b64 v[86:87], 10, v[76:77]
	v_lshl_add_u64 v[86:87], v[86:87], 2, v[72:73]
	global_store_dwordx4 v[86:87], v[66:69], off

; DI unsigned pk2(float a, float b) { f2_t v = {a, b}; return __builtin_bit_cast(unsigned, __builtin_convertvector(v, bf2_t)); }
; DI float bflo(unsigned w) { return __uint_as_float(w << 16); }
; DI float bfhi(unsigned w) { return __uint_as_float(w & 0xffff0000u); }
; DI void epi_res(f32x16 (&acc)[4][2], int m0, int n0, const float* xold, const Params& p, char* lds) {
;     ...
;   for (int pass = 0; pass < 2; ++pass) {
; #pragma unroll
;     for (int mtl = 0; mtl < 2; ++mtl)
; #pragma unroll
;       for (int nt = 0; nt < 2; ++nt)
; #pragma unroll
;         for (int g = 0; g < 4; ++g) {
;           f32x4 v; v.x = acc[pass * 2 + mtl][nt][4 * g]; v.y = acc[pass * 2 + mtl][nt][4 * g + 1]; v.z = acc[pass * 2 + mtl][nt][4 * g + 2]; v.w = acc[pass * 2 + mtl][nt][4 * g + 3];
;           *(f32x4*)(sf + (mtl * 32 + r) * 68 + nt * 32 + 8 * g + 4 * h) = v;
;         }
; #pragma unroll 4
;     for (int it = 0; it < 16; ++it) {
;       const int row_l = it * 4 + (lane >> 4);
;       const size_t grow = (size_t)(m0 + wr * 128 + pass * 64 + row_l);
;       const f32x4 a = *(const f32x4*)(sf + row_l * 68 + c4);
;       const u32x2 xw = *(const u32x2*)(p.xb + grow * 1024 + gcol);
;       f32x4 v; v.x = bflo(xw.x) + a.x; v.y = bfhi(xw.x) + a.y; v.z = bflo(xw.y) + a.z; v.w = bfhi(xw.y) + a.w;
;       if (xold) *(f32x4*)(p.out + grow * 1024 + gcol) = v;
;       u32x2 w; w.x = pk2(v.x, v.y); w.y = pk2(v.z, v.w); *(u32x2*)(p.xb + grow * 1024 + gcol) = w;
;       float sq = v.x * v.x + v.y * v.y + v.z * v.z + v.w * v.w;
;       sq += __shfl_xor(sq, 1); sq += __shfl_xor(sq, 2); sq += __shfl_xor(sq, 4); sq += __shfl_xor(sq, 8);
;       if ((lane & 15) == 0) p.ssp[grow * 16 + ((n0 + wc * 64) >> 6)] = sq;
;     }
.LBB0_277:
	s_or_b64 exec, exec, s[2:3]
	v_add_u32_e32 v76, 12, v84
	v_ashrrev_i32_e32 v77, 31, v76
	v_lshlrev_b64 v[78:79], 11, v[76:77]
	v_lshl_add_u64 v[78:79], v[70:71], 0, v[78:79]
	s_waitcnt vmcnt(11)
	v_mov_b32_e32 v84, v236
	v_mov_b32_e32 v85, v237
	v_lshl_add_u64 v[232:233], v[78:79], 0, s[96:97]
	global_load_dwordx2 v[236:237], v[232:233], off
	s_waitcnt lgkmcnt(0)
	ds_read_b128 v[66:69], v83 offset:3264
	s_and_b64 vcc, exec, s[36:37]
	v_lshlrev_b32_e32 v86, 16, v84
	v_and_b32_e32 v87, 0xffff0000, v84
	v_lshlrev_b32_e32 v84, 16, v85
	v_and_b32_e32 v85, 0xffff0000, v85
	s_waitcnt lgkmcnt(0)
	v_pk_add_f32 v[66:67], v[66:67], v[86:87]
	v_pk_add_f32 v[68:69], v[68:69], v[84:85]
	s_cbranch_vccnz .LBB0_279
	v_lshlrev_b64 v[84:85], 10, v[76:77]
	v_lshl_add_u64 v[84:85], v[84:85], 2, v[72:73]
	global_store_dwordx4 v[84:85], v[66:69], off
.LBB0_279:
	v_cvt_pk_bf16_f32 v84, v66, v67
	s_nop 0
	v_pk_mul_f32 v[66:67], v[66:67], v[66:67]
	v_cvt_pk_bf16_f32 v85, v68, v69
	v_pk_mul_f32 v[68:69], v[68:69], v[68:69]
	v_add_f32_e32 v66, v66, v67
	v_add_f32_e32 v66, v68, v66
	v_add_f32_e32 v66, v69, v66
	s_nop 1
	v_add_f32_dpp v66, v66, v66 quad_perm:[1,0,3,2] row_mask:0xf bank_mask:0xf
	global_store_dwordx2 v[78:79], v[84:85], off
	s_waitcnt lgkmcnt(0)
	s_nop 1
	v_add_f32_dpp v66, v66, v66 quad_perm:[2,3,0,1] row_mask:0xf bank_mask:0xf
	s_waitcnt lgkmcnt(0)
	s_nop 1
	v_add_f32_dpp v66, v66, v66 row_half_mirror row_mask:0xf bank_mask:0xf
	s_waitcnt lgkmcnt(0)
	s_nop 1
	v_add_f32_dpp v66, v66, v66 row_mirror row_mask:0xf bank_mask:0xf
	s_and_saveexec_b64 s[2:3], s[0:1]
	s_cbranch_execz .LBB0_264
	v_lshlrev_b64 v[68:69], 6, v[76:77]
	v_lshl_add_u64 v[68:69], v[74:75], 0, v[68:69]
	s_waitcnt lgkmcnt(0)
	global_store_dword v[68:69], v66, off
	s_branch .LBB0_264
.LBB0_281:
	v_add_u32_e32 v66, v133, v134
	s_mov_b32 s4, 0
	ds_write_b128 v66, v[50:53]
	ds_write_b128 v66, v[54:57] offset:32
	ds_write_b128 v66, v[58:61] offset:64
	ds_write_b128 v66, v[62:65] offset:96
	ds_write_b128 v66, v[34:37] offset:128
	ds_write_b128 v66, v[38:41] offset:160
	ds_write_b128 v66, v[42:45] offset:192
	ds_write_b128 v66, v[46:49] offset:224
	ds_write_b128 v66, v[18:21] offset:8704
	ds_write_b128 v66, v[22:25] offset:8736
	ds_write_b128 v66, v[26:29] offset:8768
	ds_write_b128 v66, v[30:33] offset:8800
	ds_write_b128 v66, v[2:5] offset:8832
	ds_write_b128 v66, v[6:9] offset:8864
	ds_write_b128 v66, v[10:13] offset:8896
	ds_write_b128 v66, v[14:17] offset:8928
	v_add_u32_e32 v10, 0, v81
	v_add_u32_e32 v6, 64, v10
	v_ashrrev_i32_e32 v7, 31, v6
	v_lshlrev_b64 v[8:9], 11, v[6:7]
	v_lshl_add_u64 v[8:9], v[70:71], 0, v[8:9]
	global_load_dwordx2 v[244:245], v[8:9], off
	v_add_u32_e32 v6, 0x44, v10
	v_ashrrev_i32_e32 v7, 31, v6
	v_lshlrev_b64 v[8:9], 11, v[6:7]
	v_lshl_add_u64 v[8:9], v[70:71], 0, v[8:9]
	global_load_dwordx2 v[246:247], v[8:9], off
	v_add_u32_e32 v6, 0x48, v10
	v_ashrrev_i32_e32 v7, 31, v6
	v_lshlrev_b64 v[8:9], 11, v[6:7]
	v_lshl_add_u64 v[8:9], v[70:71], 0, v[8:9]
	global_load_dwordx2 v[240:241], v[8:9], off
	v_add_u32_e32 v6, 0x4c, v10
	v_ashrrev_i32_e32 v7, 31, v6
	v_lshlrev_b64 v[8:9], 11, v[6:7]
	v_lshl_add_u64 v[8:9], v[70:71], 0, v[8:9]
	global_load_dwordx2 v[236:237], v[8:9], off
	s_waitcnt vmcnt(0)
	s_branch .LBB0_283

; DI unsigned pk2(float a, float b) { f2_t v = {a, b}; return __builtin_bit_cast(unsigned, __builtin_convertvector(v, bf2_t)); }
; DI float bflo(unsigned w) { return __uint_as_float(w << 16); }
; DI float bfhi(unsigned w) { return __uint_as_float(w & 0xffff0000u); }
; DI void epi_res(f32x16 (&acc)[4][2], int m0, int n0, const float* xold, const Params& p, char* lds) {
;     ...
;     for (int it = 0; it < 16; ++it) {
;       const int row_l = it * 4 + (lane >> 4);
;       const size_t grow = (size_t)(m0 + wr * 128 + pass * 64 + row_l);
;       const f32x4 a = *(const f32x4*)(sf + row_l * 68 + c4);
;       const u32x2 xw = *(const u32x2*)(p.xb + grow * 1024 + gcol);
;       f32x4 v; v.x = bflo(xw.x) + a.x; v.y = bfhi(xw.x) + a.y; v.z = bflo(xw.y) + a.z; v.w = bfhi(xw.y) + a.w;
;       if (xold) *(f32x4*)(p.out + grow * 1024 + gcol) = v;
;       u32x2 w; w.x = pk2(v.x, v.y); w.y = pk2(v.z, v.w); *(u32x2*)(p.xb + grow * 1024 + gcol) = w;
;       float sq = v.x * v.x + v.y * v.y + v.z * v.z + v.w * v.w;
;       sq += __shfl_xor(sq, 1); sq += __shfl_xor(sq, 2); sq += __shfl_xor(sq, 4); sq += __shfl_xor(sq, 8);
;       if ((lane & 15) == 0) p.ssp[grow * 16 + ((n0 + wc * 64) >> 6)] = sq;
;     }
.LBB0_283:
	s_cmp_eq_u32 s4, 48
	s_cselect_b32 s96, 0, 0x8000
	s_mov_b32 s97, 0
	v_add_u32_e32 v10, s4, v81
	v_add_u32_e32 v6, 64, v10
	v_ashrrev_i32_e32 v7, 31, v6
	v_lshlrev_b64 v[8:9], 11, v[6:7]
	v_lshl_add_u64 v[8:9], v[70:71], 0, v[8:9]
	s_waitcnt vmcnt(11)
	v_mov_b32_e32 v12, v244
	v_mov_b32_e32 v13, v245
	v_lshl_add_u64 v[232:233], v[8:9], 0, s[96:97]
	global_load_dwordx2 v[244:245], v[232:233], off
	s_waitcnt lgkmcnt(0)
	ds_read_b128 v[2:5], v80
	s_and_b64 vcc, exec, s[36:37]
	v_lshlrev_b32_e32 v14, 16, v12
	v_and_b32_e32 v15, 0xffff0000, v12
	v_lshlrev_b32_e32 v12, 16, v13
	v_and_b32_e32 v13, 0xffff0000, v13
	s_waitcnt lgkmcnt(0)
	v_pk_add_f32 v[2:3], v[2:3], v[14:15]
	v_pk_add_f32 v[4:5], v[4:5], v[12:13]
	s_cbranch_vccnz .LBB0_285
	v_lshlrev_b64 v[12:13], 10, v[6:7]
	v_lshl_add_u64 v[12:13], v[12:13], 2, v[72:73]
	global_store_dwordx4 v[12:13], v[2:5], off
.LBB0_285:
	v_cvt_pk_bf16_f32 v12, v2, v3
	s_nop 0
	v_pk_mul_f32 v[2:3], v[2:3], v[2:3]
	v_cvt_pk_bf16_f32 v13, v4, v5
	v_pk_mul_f32 v[4:5], v[4:5], v[4:5]
	v_add_f32_e32 v2, v2, v3
	v_add_f32_e32 v2, v4, v2
	v_add_f32_e32 v2, v5, v2
	s_nop 1
	v_add_f32_dpp v2, v2, v2 quad_perm:[1,0,3,2] row_mask:0xf bank_mask:0xf
	global_store_dwordx2 v[8:9], v[12:13], off
	s_waitcnt lgkmcnt(0)
	s_nop 1
	v_add_f32_dpp v2, v2, v2 quad_perm:[2,3,0,1] row_mask:0xf bank_mask:0xf
	s_waitcnt lgkmcnt(0)
	s_nop 1
	v_add_f32_dpp v2, v2, v2 row_half_mirror row_mask:0xf bank_mask:0xf
	s_waitcnt lgkmcnt(0)
	s_nop 1
	v_add_f32_dpp v2, v2, v2 row_mirror row_mask:0xf bank_mask:0xf
	s_and_saveexec_b64 s[2:3], s[0:1]
	s_cbranch_execz .LBB0_287
	v_lshlrev_b64 v[4:5], 6, v[6:7]
	v_lshl_add_u64 v[4:5], v[74:75], 0, v[4:5]
	s_waitcnt lgkmcnt(0)
	global_store_dword v[4:5], v2, off
.LBB0_287:
	s_or_b64 exec, exec, s[2:3]
	v_add_u32_e32 v6, 0x44, v10
	v_ashrrev_i32_e32 v7, 31, v6
	v_lshlrev_b64 v[8:9], 11, v[6:7]
	v_lshl_add_u64 v[8:9], v[70:71], 0, v[8:9]
	s_waitcnt vmcnt(11)
	v_mov_b32_e32 v12, v246
	v_mov_b32_e32 v13, v247
	v_lshl_add_u64 v[232:233], v[8:9], 0, s[96:97]
	global_load_dwordx2 v[246:247], v[232:233], off
	s_waitcnt lgkmcnt(0)
	ds_read_b128 v[2:5], v80 offset:1088
	s_and_b64 vcc, exec, s[36:37]
	v_lshlrev_b32_e32 v14, 16, v12
	v_and_b32_e32 v15, 0xffff0000, v12
	v_lshlrev_b32_e32 v12, 16, v13
	v_and_b32_e32 v13, 0xffff0000, v13
	s_waitcnt lgkmcnt(0)
	v_pk_add_f32 v[2:3], v[2:3], v[14:15]
	v_pk_add_f32 v[4:5], v[4:5], v[12:13]
	s_cbranch_vccnz .LBB0_289
	v_lshlrev_b64 v[12:13], 10, v[6:7]
	v_lshl_add_u64 v[12:13], v[12:13], 2, v[72:73]
	global_store_dwordx4 v[12:13], v[2:5], off

; DI unsigned pk2(float a, float b) { f2_t v = {a, b}; return __builtin_bit_cast(unsigned, __builtin_convertvector(v, bf2_t)); }
; DI float bflo(unsigned w) { return __uint_as_float(w << 16); }
; DI float bfhi(unsigned w) { return __uint_as_float(w & 0xffff0000u); }
; DI void epi_res(f32x16 (&acc)[4][2], int m0, int n0, const float* xold, const Params& p, char* lds) {
;     ...
;     for (int it = 0; it < 16; ++it) {
;       const int row_l = it * 4 + (lane >> 4);
;       const size_t grow = (size_t)(m0 + wr * 128 + pass * 64 + row_l);
;       const f32x4 a = *(const f32x4*)(sf + row_l * 68 + c4);
;       const u32x2 xw = *(const u32x2*)(p.xb + grow * 1024 + gcol);
;       f32x4 v; v.x = bflo(xw.x) + a.x; v.y = bfhi(xw.x) + a.y; v.z = bflo(xw.y) + a.z; v.w = bfhi(xw.y) + a.w;
;       if (xold) *(f32x4*)(p.out + grow * 1024 + gcol) = v;
;       u32x2 w; w.x = pk2(v.x, v.y); w.y = pk2(v.z, v.w); *(u32x2*)(p.xb + grow * 1024 + gcol) = w;
.LBB0_291:
	s_or_b64 exec, exec, s[2:3]
	v_add_u32_e32 v6, 0x48, v10
	v_ashrrev_i32_e32 v7, 31, v6
	v_lshlrev_b64 v[8:9], 11, v[6:7]
	v_lshl_add_u64 v[8:9], v[70:71], 0, v[8:9]
	s_waitcnt vmcnt(11)
	v_mov_b32_e32 v12, v240
	v_mov_b32_e32 v13, v241
	v_lshl_add_u64 v[232:233], v[8:9], 0, s[96:97]
	global_load_dwordx2 v[240:241], v[232:233], off
	s_waitcnt lgkmcnt(0)
	ds_read_b128 v[2:5], v80 offset:2176
	s_and_b64 vcc, exec, s[36:37]
	v_lshlrev_b32_e32 v14, 16, v12
	v_and_b32_e32 v15, 0xffff0000, v12
	v_lshlrev_b32_e32 v12, 16, v13
	v_and_b32_e32 v13, 0xffff0000, v13
	s_waitcnt lgkmcnt(0)
	v_pk_add_f32 v[2:3], v[2:3], v[14:15]
	v_pk_add_f32 v[4:5], v[4:5], v[12:13]
	s_cbranch_vccnz .LBB0_293
	v_lshlrev_b64 v[12:13], 10, v[6:7]
	v_lshl_add_u64 v[12:13], v[12:13], 2, v[72:73]
	global_store_dwordx4 v[12:13], v[2:5], off

; DI unsigned pk2(float a, float b) { f2_t v = {a, b}; return __builtin_bit_cast(unsigned, __builtin_convertvector(v, bf2_t)); }
; DI float bflo(unsigned w) { return __uint_as_float(w << 16); }
; DI float bfhi(unsigned w) { return __uint_as_float(w & 0xffff0000u); }
; DI void epi_res(f32x16 (&acc)[4][2], int m0, int n0, const float* xold, const Params& p, char* lds) {
;     ...
;     for (int it = 0; it < 16; ++it) {
;       const int row_l = it * 4 + (lane >> 4);
;       const size_t grow = (size_t)(m0 + wr * 128 + pass * 64 + row_l);
;       const f32x4 a = *(const f32x4*)(sf + row_l * 68 + c4);
;       const u32x2 xw = *(const u32x2*)(p.xb + grow * 1024 + gcol);
;       f32x4 v; v.x = bflo(xw.x) + a.x; v.y = bfhi(xw.x) + a.y; v.z = bflo(xw.y) + a.z; v.w = bfhi(xw.y) + a.w;
;       if (xold) *(f32x4*)(p.out + grow * 1024 + gcol) = v;
;       u32x2 w; w.x = pk2(v.x, v.y); w.y = pk2(v.z, v.w); *(u32x2*)(p.xb + grow * 1024 + gcol) = w;
;       float sq = v.x * v.x + v.y * v.y + v.z * v.z + v.w * v.w;
;       sq += __shfl_xor(sq, 1); sq += __shfl_xor(sq, 2); sq += __shfl_xor(sq, 4); sq += __shfl_xor(sq, 8);
;       if ((lane & 15) == 0) p.ssp[grow * 16 + ((n0 + wc * 64) >> 6)] = sq;
;     }
.LBB0_295:
	s_or_b64 exec, exec, s[2:3]
	v_add_u32_e32 v6, 0x4c, v10
	v_ashrrev_i32_e32 v7, 31, v6
	v_lshlrev_b64 v[8:9], 11, v[6:7]
	v_lshl_add_u64 v[8:9], v[70:71], 0, v[8:9]
	s_waitcnt vmcnt(11)
	v_mov_b32_e32 v10, v236
	v_mov_b32_e32 v11, v237
	v_lshl_add_u64 v[232:233], v[8:9], 0, s[96:97]
	global_load_dwordx2 v[236:237], v[232:233], off
	s_waitcnt lgkmcnt(0)
	ds_read_b128 v[2:5], v80 offset:3264
	s_and_b64 vcc, exec, s[36:37]
	v_lshlrev_b32_e32 v12, 16, v10
	v_and_b32_e32 v13, 0xffff0000, v10
	v_lshlrev_b32_e32 v10, 16, v11
	v_and_b32_e32 v11, 0xffff0000, v11
	s_waitcnt lgkmcnt(0)
	v_pk_add_f32 v[2:3], v[2:3], v[12:13]
	v_pk_add_f32 v[4:5], v[4:5], v[10:11]
	s_cbranch_vccnz .LBB0_297
	v_lshlrev_b64 v[10:11], 10, v[6:7]
	v_lshl_add_u64 v[10:11], v[10:11], 2, v[72:73]
	global_store_dwordx4 v[10:11], v[2:5], off
.LBB0_297:
	v_cvt_pk_bf16_f32 v10, v2, v3
	s_nop 0
	v_pk_mul_f32 v[2:3], v[2:3], v[2:3]
	v_cvt_pk_bf16_f32 v11, v4, v5
	v_pk_mul_f32 v[4:5], v[4:5], v[4:5]
	v_add_f32_e32 v2, v2, v3
	v_add_f32_e32 v2, v4, v2
	v_add_f32_e32 v2, v5, v2
	s_nop 1
	v_add_f32_dpp v2, v2, v2 quad_perm:[1,0,3,2] row_mask:0xf bank_mask:0xf
	global_store_dwordx2 v[8:9], v[10:11], off
	s_waitcnt lgkmcnt(0)
	s_nop 1
	v_add_f32_dpp v2, v2, v2 quad_perm:[2,3,0,1] row_mask:0xf bank_mask:0xf
	s_waitcnt lgkmcnt(0)
	s_nop 1
	v_add_f32_dpp v2, v2, v2 row_half_mirror row_mask:0xf bank_mask:0xf
	s_waitcnt lgkmcnt(0)
	s_nop 1
	v_add_f32_dpp v2, v2, v2 row_mirror row_mask:0xf bank_mask:0xf
	s_and_saveexec_b64 s[2:3], s[0:1]
	s_cbranch_execz .LBB0_282
	v_lshlrev_b64 v[4:5], 6, v[6:7]
	v_lshl_add_u64 v[4:5], v[74:75], 0, v[4:5]
	s_waitcnt lgkmcnt(0)
	global_store_dword v[4:5], v2, off
	s_branch .LBB0_282

; DI void epi_res(f32x16 (&acc)[4][2], int m0, int n0, const float* xold, const Params& p, char* lds) {
;     ...
;   const int c4 = (lane & 15) * 4, gcol = n0 + wc * 64 + c4;
; #pragma unroll
;   for (int pass = 0; pass < 2; ++pass) {
; #pragma unroll
;     for (int mtl = 0; mtl < 2; ++mtl)
; #pragma unroll
;       for (int nt = 0; nt < 2; ++nt)
; #pragma unroll
;         for (int g = 0; g < 4; ++g) {
;           f32x4 v; v.x = acc[pass * 2 + mtl][nt][4 * g]; v.y = acc[pass * 2 + mtl][nt][4 * g + 1]; v.z = acc[pass * 2 + mtl][nt][4 * g + 2]; v.w = acc[pass * 2 + mtl][nt][4 * g + 3];
;           *(f32x4*)(sf + (mtl * 32 + r) * 68 + nt * 32 + 8 * g + 4 * h) = v;
;         }
; #pragma unroll 4
;     for (int it = 0; it < 16; ++it) {
;       const int row_l = it * 4 + (lane >> 4);
;       const size_t grow = (size_t)(m0 + wr * 128 + pass * 64 + row_l);
;       const f32x4 a = *(const f32x4*)(sf + row_l * 68 + c4);
;       const u32x2 xw = *(const u32x2*)(p.xb + grow * 1024 + gcol);
.LBB0_445:
	v_mov_b32_e32 v0, v227
	s_movk_i32 s8, 0x4800
	v_lshrrev_b32_e32 v130, 6, v0
	v_mul_lo_u32 v140, v130, s8
	v_and_b32_e32 v130, 0xc0, v0
	v_or_b32_e32 v134, s7, v130
	v_lshrrev_b32_e32 v130, 1, v0
	v_and_b32_e32 v135, 31, v0
	v_and_b32_e32 v141, 15, v0
	v_and_or_b32 v133, v130, 16, v140
	v_bfe_u32 v142, v0, 4, 2
	v_ashrrev_i32_e32 v0, 1, v0
	v_and_b32_e32 v130, 64, v239
	v_and_b32_e32 v143, 0xffffff80, v0
	v_xor_b32_e32 v0, 1, v239
	v_add_u32_e32 v132, 64, v130
	v_cmp_lt_i32_e32 vcc, v0, v132
	v_xor_b32_e32 v130, 2, v239
	v_xor_b32_e32 v131, 4, v239
	v_cndmask_b32_e32 v0, v239, v0, vcc
	v_cmp_lt_i32_e32 vcc, v130, v132
	v_xor_b32_e32 v138, 8, v239
	s_movk_i32 s8, 0x110
	v_cndmask_b32_e32 v130, v239, v130, vcc
	v_cmp_lt_i32_e32 vcc, v131, v132
	v_lshl_or_b32 v136, v141, 2, v134
	s_and_b32 s34, s4, 7
	v_cndmask_b32_e32 v131, v239, v131, vcc
	v_cmp_lt_i32_e32 vcc, v138, v132
	s_lshl_b32 s2, s2, 14
	s_lshl_b32 s3, s3, 11
	v_cndmask_b32_e32 v132, v239, v138, vcc
	v_ashrrev_i32_e32 v138, 6, v134
	v_mul_u32_u24_e32 v134, 0x110, v135
	v_mad_u32_u24 v135, v135, s8, v133
	ds_write_b128 v135, v[114:117]
	ds_write_b128 v135, v[118:121] offset:32
	ds_write_b128 v135, v[122:125] offset:64
	ds_write_b128 v135, v[126:129] offset:96
	ds_write_b128 v135, v[98:101] offset:128
	ds_write_b128 v135, v[102:105] offset:160
	ds_write_b128 v135, v[106:109] offset:192
	ds_write_b128 v135, v[110:113] offset:224
	ds_write_b128 v135, v[82:85] offset:8704
	ds_write_b128 v135, v[86:89] offset:8736
	ds_write_b128 v135, v[90:93] offset:8768
	ds_write_b128 v135, v[94:97] offset:8800
	ds_write_b128 v135, v[66:69] offset:8832
	ds_write_b128 v135, v[70:73] offset:8864
	ds_write_b128 v135, v[74:77] offset:8896
	ds_write_b128 v135, v[78:81] offset:8928
	v_mul_u32_u24_e32 v70, 0x110, v142
	s_lshl_b32 s35, s34, 8
	v_or_b32_e32 v70, v140, v70
	s_add_i32 s6, s6, s34
	s_add_i32 s2, s2, s3
	v_readlane_b32 s8, v253, 36
	v_lshl_add_u32 v72, v141, 4, v70
	v_lshl_add_u32 v70, s6, 8, v143
	s_or_b32 s2, s2, s35
	v_ashrrev_i32_e32 v137, 31, v136
	v_ashrrev_i32_e32 v139, 31, v138
	v_readlane_b32 s16, v253, 44
	v_readlane_b32 s17, v253, 45
	v_or_b32_e32 v73, v70, v142
	v_add_u32_e32 v70, s2, v143
	s_mov_b32 s7, 0
	v_lshlrev_b32_e32 v0, 2, v0
	v_lshlrev_b32_e32 v130, 2, v130
	v_lshlrev_b32_e32 v131, 2, v131
	v_lshlrev_b32_e32 v132, 2, v132
	v_cmp_eq_u32_e32 vcc, 0, v141
	v_lshl_add_u64 v[66:67], v[136:137], 1, s[16:17]
	v_lshl_add_u64 v[68:69], v[138:139], 2, s[70:71]
	v_or_b32_e32 v74, v70, v142
	v_mov_b32_e32 v75, v72
	v_readlane_b32 s9, v253, 37
	v_readlane_b32 s10, v253, 38
	v_readlane_b32 s11, v253, 39
	v_readlane_b32 s12, v253, 40
	v_readlane_b32 s13, v253, 41
	v_readlane_b32 s14, v253, 42
	v_readlane_b32 s15, v253, 43
	v_readlane_b32 s18, v253, 46
	v_readlane_b32 s19, v253, 47
	v_readlane_b32 s20, v253, 48
	v_readlane_b32 s21, v253, 49
	v_readlane_b32 s22, v253, 50
	v_readlane_b32 s23, v253, 51
	v_add_u32_e32 v70, 0, v74
	v_ashrrev_i32_e32 v71, 31, v70
	v_lshlrev_b64 v[80:81], 11, v[70:71]
	v_lshl_add_u64 v[80:81], v[66:67], 0, v[80:81]
	global_load_dwordx2 v[244:245], v[80:81], off
	v_add_u32_e32 v76, 0, v73
	v_add_u32_e32 v70, 4, v76
	v_ashrrev_i32_e32 v71, 31, v70
	v_lshlrev_b64 v[82:83], 11, v[70:71]
	v_lshl_add_u64 v[82:83], v[66:67], 0, v[82:83]
	global_load_dwordx2 v[246:247], v[82:83], off
	v_add_u32_e32 v70, 8, v76
	v_ashrrev_i32_e32 v71, 31, v70
	v_lshlrev_b64 v[82:83], 11, v[70:71]
	v_lshl_add_u64 v[82:83], v[66:67], 0, v[82:83]
	global_load_dwordx2 v[240:241], v[82:83], off
	v_add_u32_e32 v70, 12, v76
	v_ashrrev_i32_e32 v71, 31, v70
	v_lshlrev_b64 v[80:81], 11, v[70:71]
	v_lshl_add_u64 v[80:81], v[66:67], 0, v[80:81]
	global_load_dwordx2 v[236:237], v[80:81], off
	s_waitcnt vmcnt(0)
	s_branch .LBB0_447

; DI unsigned pk2(float a, float b) { f2_t v = {a, b}; return __builtin_bit_cast(unsigned, __builtin_convertvector(v, bf2_t)); }
; DI float bflo(unsigned w) { return __uint_as_float(w << 16); }
; DI float bfhi(unsigned w) { return __uint_as_float(w & 0xffff0000u); }
; DI void epi_res(f32x16 (&acc)[4][2], int m0, int n0, const float* xold, const Params& p, char* lds) {
;     ...
;     for (int it = 0; it < 16; ++it) {
;       const int row_l = it * 4 + (lane >> 4);
;       const size_t grow = (size_t)(m0 + wr * 128 + pass * 64 + row_l);
;       const f32x4 a = *(const f32x4*)(sf + row_l * 68 + c4);
;       const u32x2 xw = *(const u32x2*)(p.xb + grow * 1024 + gcol);
;       f32x4 v; v.x = bflo(xw.x) + a.x; v.y = bfhi(xw.x) + a.y; v.z = bflo(xw.y) + a.z; v.w = bfhi(xw.y) + a.w;
;       if (xold) *(f32x4*)(p.out + grow * 1024 + gcol) = v;
;       u32x2 w; w.x = pk2(v.x, v.y); w.y = pk2(v.z, v.w); *(u32x2*)(p.xb + grow * 1024 + gcol) = w;
;       float sq = v.x * v.x + v.y * v.y + v.z * v.z + v.w * v.w;
;       sq += __shfl_xor(sq, 1); sq += __shfl_xor(sq, 2); sq += __shfl_xor(sq, 4); sq += __shfl_xor(sq, 8);
;       if ((lane & 15) == 0) p.ssp[grow * 16 + ((n0 + wc * 64) >> 6)] = sq;
;     }
.LBB0_447:
	s_cmp_eq_u32 s7, 48
	s_cselect_b32 s96, 0, 0x8000
	s_mov_b32 s97, 0
	v_add_u32_e32 v70, s7, v74
	v_ashrrev_i32_e32 v71, 31, v70
	v_lshlrev_b64 v[80:81], 11, v[70:71]
	v_lshl_add_u64 v[80:81], v[66:67], 0, v[80:81]
	s_waitcnt vmcnt(11)
	v_mov_b32_e32 v82, v244
	v_mov_b32_e32 v83, v245
	v_lshl_add_u64 v[232:233], v[80:81], 0, s[96:97]
	global_load_dwordx2 v[244:245], v[232:233], off
	s_waitcnt lgkmcnt(0)
	ds_read_b128 v[76:79], v75
	v_lshlrev_b32_e32 v84, 16, v82
	v_and_b32_e32 v85, 0xffff0000, v82
	s_waitcnt lgkmcnt(0)
	v_pk_add_f32 v[76:77], v[76:77], v[84:85]
	v_lshlrev_b32_e32 v82, 16, v83
	v_and_b32_e32 v83, 0xffff0000, v83
	v_pk_add_f32 v[78:79], v[78:79], v[82:83]
	v_cvt_pk_bf16_f32 v82, v76, v77
	v_pk_mul_f32 v[76:77], v[76:77], v[76:77]
	v_cvt_pk_bf16_f32 v83, v78, v79
	v_pk_mul_f32 v[78:79], v[78:79], v[78:79]
	v_add_f32_e32 v76, v76, v77
	v_add_f32_e32 v76, v78, v76
	v_add_f32_e32 v76, v79, v76
	s_nop 1
	v_add_f32_dpp v76, v76, v76 quad_perm:[1,0,3,2] row_mask:0xf bank_mask:0xf
	global_store_dwordx2 v[80:81], v[82:83], off
	s_waitcnt lgkmcnt(0)
	s_nop 1
	v_add_f32_dpp v76, v76, v76 quad_perm:[2,3,0,1] row_mask:0xf bank_mask:0xf
	s_waitcnt lgkmcnt(0)
	s_nop 1
	v_add_f32_dpp v76, v76, v76 row_half_mirror row_mask:0xf bank_mask:0xf
	s_waitcnt lgkmcnt(0)
	s_nop 1
	v_add_f32_dpp v76, v76, v76 row_mirror row_mask:0xf bank_mask:0xf
	s_and_saveexec_b64 s[2:3], vcc
	s_cbranch_execz .LBB0_449
	v_lshlrev_b64 v[70:71], 6, v[70:71]
	v_lshl_add_u64 v[70:71], v[68:69], 0, v[70:71]
	s_waitcnt lgkmcnt(0)
	global_store_dword v[70:71], v76, off
.LBB0_449:
	s_or_b64 exec, exec, s[2:3]
	v_add_u32_e32 v76, s7, v73
	v_add_u32_e32 v70, 4, v76
	v_ashrrev_i32_e32 v71, 31, v70
	v_lshlrev_b64 v[82:83], 11, v[70:71]
	v_lshl_add_u64 v[82:83], v[66:67], 0, v[82:83]
	s_waitcnt vmcnt(11)
	v_mov_b32_e32 v84, v246
	v_mov_b32_e32 v85, v247
	v_lshl_add_u64 v[232:233], v[82:83], 0, s[96:97]
	global_load_dwordx2 v[246:247], v[232:233], off
	ds_read_b128 v[78:81], v75 offset:1088
	v_lshlrev_b32_e32 v86, 16, v84
	v_and_b32_e32 v87, 0xffff0000, v84
	s_waitcnt lgkmcnt(0)
	v_pk_add_f32 v[78:79], v[78:79], v[86:87]
	v_lshlrev_b32_e32 v84, 16, v85
	v_and_b32_e32 v85, 0xffff0000, v85
	v_pk_add_f32 v[80:81], v[80:81], v[84:85]
	v_cvt_pk_bf16_f32 v84, v78, v79
	v_pk_mul_f32 v[78:79], v[78:79], v[78:79]
	v_cvt_pk_bf16_f32 v85, v80, v81
	v_pk_mul_f32 v[80:81], v[80:81], v[80:81]
	v_add_f32_e32 v77, v78, v79
	v_add_f32_e32 v77, v80, v77
	v_add_f32_e32 v77, v81, v77
	s_nop 1
	v_add_f32_dpp v77, v77, v77 quad_perm:[1,0,3,2] row_mask:0xf bank_mask:0xf
	global_store_dwordx2 v[82:83], v[84:85], off
	s_waitcnt lgkmcnt(0)
	s_nop 1
	v_add_f32_dpp v77, v77, v77 quad_perm:[2,3,0,1] row_mask:0xf bank_mask:0xf
	s_waitcnt lgkmcnt(0)
	s_nop 1
	v_add_f32_dpp v77, v77, v77 row_half_mirror row_mask:0xf bank_mask:0xf
	s_waitcnt lgkmcnt(0)
	s_nop 1
	v_add_f32_dpp v77, v77, v77 row_mirror row_mask:0xf bank_mask:0xf
	s_and_saveexec_b64 s[2:3], vcc
	s_cbranch_execz .LBB0_451
	v_lshlrev_b64 v[70:71], 6, v[70:71]
	v_lshl_add_u64 v[70:71], v[68:69], 0, v[70:71]
	s_waitcnt lgkmcnt(0)
	global_store_dword v[70:71], v77, off
; DI unsigned pk2(float a, float b) { f2_t v = {a, b}; return __builtin_bit_cast(unsigned, __builtin_convertvector(v, bf2_t)); }
; DI float bflo(unsigned w) { return __uint_as_float(w << 16); }
; DI float bfhi(unsigned w) { return __uint_as_float(w & 0xffff0000u); }
; DI void epi_res(f32x16 (&acc)[4][2], int m0, int n0, const float* xold, const Params& p, char* lds) {
;     ...
;   for (int pass = 0; pass < 2; ++pass) {
; #pragma unroll
;     for (int mtl = 0; mtl < 2; ++mtl)
; #pragma unroll
;       for (int nt = 0; nt < 2; ++nt)
; #pragma unroll
;         for (int g = 0; g < 4; ++g) {
;           f32x4 v; v.x = acc[pass * 2 + mtl][nt][4 * g]; v.y = acc[pass * 2 + mtl][nt][4 * g + 1]; v.z = acc[pass * 2 + mtl][nt][4 * g + 2]; v.w = acc[pass * 2 + mtl][nt][4 * g + 3];
;           *(f32x4*)(sf + (mtl * 32 + r) * 68 + nt * 32 + 8 * g + 4 * h) = v;
;         }
; #pragma unroll 4
;     for (int it = 0; it < 16; ++it) {
;       const int row_l = it * 4 + (lane >> 4);
;       const size_t grow = (size_t)(m0 + wr * 128 + pass * 64 + row_l);
;       const f32x4 a = *(const f32x4*)(sf + row_l * 68 + c4);
;       const u32x2 xw = *(const u32x2*)(p.xb + grow * 1024 + gcol);
;       f32x4 v; v.x = bflo(xw.x) + a.x; v.y = bfhi(xw.x) + a.y; v.z = bflo(xw.y) + a.z; v.w = bfhi(xw.y) + a.w;
;       if (xold) *(f32x4*)(p.out + grow * 1024 + gcol) = v;
;       u32x2 w; w.x = pk2(v.x, v.y); w.y = pk2(v.z, v.w); *(u32x2*)(p.xb + grow * 1024 + gcol) = w;
;       float sq = v.x * v.x + v.y * v.y + v.z * v.z + v.w * v.w;
;       sq += __shfl_xor(sq, 1); sq += __shfl_xor(sq, 2); sq += __shfl_xor(sq, 4); sq += __shfl_xor(sq, 8);
;       if ((lane & 15) == 0) p.ssp[grow * 16 + ((n0 + wc * 64) >> 6)] = sq;
;     }
.LBB0_451:
	s_or_b64 exec, exec, s[2:3]
	v_add_u32_e32 v70, 8, v76
	v_ashrrev_i32_e32 v71, 31, v70
	v_lshlrev_b64 v[82:83], 11, v[70:71]
	v_lshl_add_u64 v[82:83], v[66:67], 0, v[82:83]
	s_waitcnt vmcnt(11)
	v_mov_b32_e32 v84, v240
	v_mov_b32_e32 v85, v241
	v_lshl_add_u64 v[232:233], v[82:83], 0, s[96:97]
	global_load_dwordx2 v[240:241], v[232:233], off
	s_waitcnt lgkmcnt(0)
	ds_read_b128 v[78:81], v75 offset:2176
	v_lshlrev_b32_e32 v86, 16, v84
	v_and_b32_e32 v87, 0xffff0000, v84
	s_waitcnt lgkmcnt(0)
	v_pk_add_f32 v[78:79], v[78:79], v[86:87]
	v_lshlrev_b32_e32 v84, 16, v85
	v_and_b32_e32 v85, 0xffff0000, v85
	v_pk_add_f32 v[80:81], v[80:81], v[84:85]
	v_cvt_pk_bf16_f32 v84, v78, v79
	v_pk_mul_f32 v[78:79], v[78:79], v[78:79]
	v_cvt_pk_bf16_f32 v85, v80, v81
	v_pk_mul_f32 v[80:81], v[80:81], v[80:81]
	v_add_f32_e32 v77, v78, v79
	v_add_f32_e32 v77, v80, v77
	v_add_f32_e32 v77, v81, v77
	s_nop 1
	v_add_f32_dpp v77, v77, v77 quad_perm:[1,0,3,2] row_mask:0xf bank_mask:0xf
	global_store_dwordx2 v[82:83], v[84:85], off
	s_waitcnt lgkmcnt(0)
	s_nop 1
	v_add_f32_dpp v77, v77, v77 quad_perm:[2,3,0,1] row_mask:0xf bank_mask:0xf
	s_waitcnt lgkmcnt(0)
	s_nop 1
	v_add_f32_dpp v77, v77, v77 row_half_mirror row_mask:0xf bank_mask:0xf
	s_waitcnt lgkmcnt(0)
	s_nop 1
	v_add_f32_dpp v77, v77, v77 row_mirror row_mask:0xf bank_mask:0xf
	s_and_saveexec_b64 s[2:3], vcc
	s_cbranch_execz .LBB0_453
	v_lshlrev_b64 v[70:71], 6, v[70:71]
	v_lshl_add_u64 v[70:71], v[68:69], 0, v[70:71]
	s_waitcnt lgkmcnt(0)
	global_store_dword v[70:71], v77, off
.LBB0_453:
	s_or_b64 exec, exec, s[2:3]
	v_add_u32_e32 v70, 12, v76
	v_ashrrev_i32_e32 v71, 31, v70
	v_lshlrev_b64 v[80:81], 11, v[70:71]
	v_lshl_add_u64 v[80:81], v[66:67], 0, v[80:81]
	s_waitcnt vmcnt(11)
	v_mov_b32_e32 v82, v236
	v_mov_b32_e32 v83, v237
	v_lshl_add_u64 v[232:233], v[80:81], 0, s[96:97]
	global_load_dwordx2 v[236:237], v[232:233], off
	s_waitcnt lgkmcnt(0)
	ds_read_b128 v[76:79], v75 offset:3264
	v_lshlrev_b32_e32 v84, 16, v82
	v_and_b32_e32 v85, 0xffff0000, v82
	s_waitcnt lgkmcnt(0)
	v_pk_add_f32 v[76:77], v[76:77], v[84:85]
	v_lshlrev_b32_e32 v82, 16, v83
	v_and_b32_e32 v83, 0xffff0000, v83
	v_pk_add_f32 v[78:79], v[78:79], v[82:83]
	v_cvt_pk_bf16_f32 v82, v76, v77
	v_pk_mul_f32 v[76:77], v[76:77], v[76:77]
	v_cvt_pk_bf16_f32 v83, v78, v79
	v_pk_mul_f32 v[78:79], v[78:79], v[78:79]
	v_add_f32_e32 v76, v76, v77
	v_add_f32_e32 v76, v78, v76
	v_add_f32_e32 v76, v79, v76
	s_nop 1
	v_add_f32_dpp v76, v76, v76 quad_perm:[1,0,3,2] row_mask:0xf bank_mask:0xf
	global_store_dwordx2 v[80:81], v[82:83], off
	s_waitcnt lgkmcnt(0)
	s_nop 1
	v_add_f32_dpp v76, v76, v76 quad_perm:[2,3,0,1] row_mask:0xf bank_mask:0xf
	s_waitcnt lgkmcnt(0)
	s_nop 1
	v_add_f32_dpp v76, v76, v76 row_half_mirror row_mask:0xf bank_mask:0xf
	s_waitcnt lgkmcnt(0)
	s_nop 1
	v_add_f32_dpp v76, v76, v76 row_mirror row_mask:0xf bank_mask:0xf
	s_and_saveexec_b64 s[2:3], vcc
	s_cbranch_execz .LBB0_446
	v_lshlrev_b64 v[70:71], 6, v[70:71]
	v_lshl_add_u64 v[70:71], v[68:69], 0, v[70:71]
	s_waitcnt lgkmcnt(0)
	global_store_dword v[70:71], v76, off
	s_branch .LBB0_446
.LBB0_455:
	v_add_u32_e32 v70, v133, v134
	s_mov_b32 s6, 0
	ds_write_b128 v70, v[50:53]
	ds_write_b128 v70, v[54:57] offset:32
	ds_write_b128 v70, v[58:61] offset:64
	ds_write_b128 v70, v[62:65] offset:96
	ds_write_b128 v70, v[34:37] offset:128
	ds_write_b128 v70, v[38:41] offset:160
	ds_write_b128 v70, v[42:45] offset:192
	ds_write_b128 v70, v[46:49] offset:224
	ds_write_b128 v70, v[18:21] offset:8704
	ds_write_b128 v70, v[22:25] offset:8736
	ds_write_b128 v70, v[26:29] offset:8768
	ds_write_b128 v70, v[30:33] offset:8800
	ds_write_b128 v70, v[2:5] offset:8832
	ds_write_b128 v70, v[6:9] offset:8864
	ds_write_b128 v70, v[10:13] offset:8896
	ds_write_b128 v70, v[14:17] offset:8928
	v_add_u32_e32 v4, 0, v73
	v_add_u32_e32 v2, 64, v4
	v_ashrrev_i32_e32 v3, 31, v2
	v_lshlrev_b64 v[10:11], 11, v[2:3]
	v_lshl_add_u64 v[10:11], v[66:67], 0, v[10:11]
	global_load_dwordx2 v[244:245], v[10:11], off
	v_add_u32_e32 v2, 0x44, v4
	v_ashrrev_i32_e32 v3, 31, v2
	v_lshlrev_b64 v[10:11], 11, v[2:3]
	v_lshl_add_u64 v[10:11], v[66:67], 0, v[10:11]
	global_load_dwordx2 v[246:247], v[10:11], off
	v_add_u32_e32 v2, 0x48, v4
	v_ashrrev_i32_e32 v3, 31, v2
	v_lshlrev_b64 v[10:11], 11, v[2:3]
	v_lshl_add_u64 v[10:11], v[66:67], 0, v[10:11]
	global_load_dwordx2 v[240:241], v[10:11], off
	v_add_u32_e32 v2, 0x4c, v4
	v_ashrrev_i32_e32 v3, 31, v2
	v_lshlrev_b64 v[8:9], 11, v[2:3]
	v_lshl_add_u64 v[8:9], v[66:67], 0, v[8:9]
	global_load_dwordx2 v[236:237], v[8:9], off
	s_waitcnt vmcnt(0)
	s_branch .LBB0_457

; DI unsigned pk2(float a, float b) { f2_t v = {a, b}; return __builtin_bit_cast(unsigned, __builtin_convertvector(v, bf2_t)); }
; DI float bflo(unsigned w) { return __uint_as_float(w << 16); }
; DI float bfhi(unsigned w) { return __uint_as_float(w & 0xffff0000u); }
; DI void epi_res(f32x16 (&acc)[4][2], int m0, int n0, const float* xold, const Params& p, char* lds) {
;     ...
;     for (int it = 0; it < 16; ++it) {
;       const int row_l = it * 4 + (lane >> 4);
;       const size_t grow = (size_t)(m0 + wr * 128 + pass * 64 + row_l);
;       const f32x4 a = *(const f32x4*)(sf + row_l * 68 + c4);
;       const u32x2 xw = *(const u32x2*)(p.xb + grow * 1024 + gcol);
;       f32x4 v; v.x = bflo(xw.x) + a.x; v.y = bfhi(xw.x) + a.y; v.z = bflo(xw.y) + a.z; v.w = bfhi(xw.y) + a.w;
;       if (xold) *(f32x4*)(p.out + grow * 1024 + gcol) = v;
;       u32x2 w; w.x = pk2(v.x, v.y); w.y = pk2(v.z, v.w); *(u32x2*)(p.xb + grow * 1024 + gcol) = w;
;       float sq = v.x * v.x + v.y * v.y + v.z * v.z + v.w * v.w;
;       sq += __shfl_xor(sq, 1); sq += __shfl_xor(sq, 2); sq += __shfl_xor(sq, 4); sq += __shfl_xor(sq, 8);
;       if ((lane & 15) == 0) p.ssp[grow * 16 + ((n0 + wc * 64) >> 6)] = sq;
;     }
.LBB0_457:
	s_cmp_eq_u32 s6, 48
	s_cselect_b32 s96, 0, 0x8000
	s_mov_b32 s97, 0
	v_add_u32_e32 v4, s6, v73
	v_add_u32_e32 v2, 64, v4
	v_ashrrev_i32_e32 v3, 31, v2
	v_lshlrev_b64 v[10:11], 11, v[2:3]
	v_lshl_add_u64 v[10:11], v[66:67], 0, v[10:11]
	s_waitcnt vmcnt(11)
	v_mov_b32_e32 v12, v244
	v_mov_b32_e32 v13, v245
	v_lshl_add_u64 v[232:233], v[10:11], 0, s[96:97]
	global_load_dwordx2 v[244:245], v[232:233], off
	ds_read_b128 v[6:9], v72
	v_lshlrev_b32_e32 v14, 16, v12
	v_and_b32_e32 v15, 0xffff0000, v12
	s_waitcnt lgkmcnt(0)
	v_pk_add_f32 v[6:7], v[6:7], v[14:15]
	v_lshlrev_b32_e32 v12, 16, v13
	v_and_b32_e32 v13, 0xffff0000, v13
	v_pk_add_f32 v[8:9], v[8:9], v[12:13]
	v_cvt_pk_bf16_f32 v12, v6, v7
	v_pk_mul_f32 v[6:7], v[6:7], v[6:7]
	v_cvt_pk_bf16_f32 v13, v8, v9
	v_pk_mul_f32 v[8:9], v[8:9], v[8:9]
	v_add_f32_e32 v5, v6, v7
	v_add_f32_e32 v5, v8, v5
	v_add_f32_e32 v5, v9, v5
	s_nop 1
	v_add_f32_dpp v5, v5, v5 quad_perm:[1,0,3,2] row_mask:0xf bank_mask:0xf
	global_store_dwordx2 v[10:11], v[12:13], off
	s_waitcnt lgkmcnt(0)
	s_nop 1
	v_add_f32_dpp v5, v5, v5 quad_perm:[2,3,0,1] row_mask:0xf bank_mask:0xf
	s_waitcnt lgkmcnt(0)
	s_nop 1
	v_add_f32_dpp v5, v5, v5 row_half_mirror row_mask:0xf bank_mask:0xf
	s_waitcnt lgkmcnt(0)
	s_nop 1
	v_add_f32_dpp v5, v5, v5 row_mirror row_mask:0xf bank_mask:0xf
	s_and_saveexec_b64 s[2:3], vcc
	s_cbranch_execz .LBB0_459
	v_lshlrev_b64 v[2:3], 6, v[2:3]
	v_lshl_add_u64 v[2:3], v[68:69], 0, v[2:3]
	s_waitcnt lgkmcnt(0)
	global_store_dword v[2:3], v5, off
.LBB0_459:
	s_or_b64 exec, exec, s[2:3]
	v_add_u32_e32 v2, 0x44, v4
	v_ashrrev_i32_e32 v3, 31, v2
	v_lshlrev_b64 v[10:11], 11, v[2:3]
	v_lshl_add_u64 v[10:11], v[66:67], 0, v[10:11]
	s_waitcnt vmcnt(11)
	v_mov_b32_e32 v12, v246
	v_mov_b32_e32 v13, v247
	v_lshl_add_u64 v[232:233], v[10:11], 0, s[96:97]
	global_load_dwordx2 v[246:247], v[232:233], off
	s_waitcnt lgkmcnt(0)
	ds_read_b128 v[6:9], v72 offset:1088
	v_lshlrev_b32_e32 v14, 16, v12
	v_and_b32_e32 v15, 0xffff0000, v12
	s_waitcnt lgkmcnt(0)
	v_pk_add_f32 v[6:7], v[6:7], v[14:15]
	v_lshlrev_b32_e32 v12, 16, v13
	v_and_b32_e32 v13, 0xffff0000, v13
	v_pk_add_f32 v[8:9], v[8:9], v[12:13]
	v_cvt_pk_bf16_f32 v12, v6, v7
	v_pk_mul_f32 v[6:7], v[6:7], v[6:7]
	v_cvt_pk_bf16_f32 v13, v8, v9
	v_pk_mul_f32 v[8:9], v[8:9], v[8:9]
	v_add_f32_e32 v5, v6, v7
	v_add_f32_e32 v5, v8, v5
	v_add_f32_e32 v5, v9, v5
	s_nop 1
	v_add_f32_dpp v5, v5, v5 quad_perm:[1,0,3,2] row_mask:0xf bank_mask:0xf
	global_store_dwordx2 v[10:11], v[12:13], off
	s_waitcnt lgkmcnt(0)
	s_nop 1
	v_add_f32_dpp v5, v5, v5 quad_perm:[2,3,0,1] row_mask:0xf bank_mask:0xf
	s_waitcnt lgkmcnt(0)
	s_nop 1
	v_add_f32_dpp v5, v5, v5 row_half_mirror row_mask:0xf bank_mask:0xf
	s_waitcnt lgkmcnt(0)
	s_nop 1
	v_add_f32_dpp v5, v5, v5 row_mirror row_mask:0xf bank_mask:0xf
	s_and_saveexec_b64 s[2:3], vcc
	s_cbranch_execz .LBB0_461
	v_lshlrev_b64 v[2:3], 6, v[2:3]
	v_lshl_add_u64 v[2:3], v[68:69], 0, v[2:3]
	s_waitcnt lgkmcnt(0)
	global_store_dword v[2:3], v5, off
.LBB0_461:
	s_or_b64 exec, exec, s[2:3]
	v_add_u32_e32 v2, 0x48, v4
	v_ashrrev_i32_e32 v3, 31, v2
	v_lshlrev_b64 v[10:11], 11, v[2:3]
	v_lshl_add_u64 v[10:11], v[66:67], 0, v[10:11]
	s_waitcnt vmcnt(11)
	v_mov_b32_e32 v12, v240
	v_mov_b32_e32 v13, v241
	v_lshl_add_u64 v[232:233], v[10:11], 0, s[96:97]
	global_load_dwordx2 v[240:241], v[232:233], off
	s_waitcnt lgkmcnt(0)
	ds_read_b128 v[6:9], v72 offset:2176
	v_lshlrev_b32_e32 v14, 16, v12
	v_and_b32_e32 v15, 0xffff0000, v12
	s_waitcnt lgkmcnt(0)
	v_pk_add_f32 v[6:7], v[6:7], v[14:15]
	v_lshlrev_b32_e32 v12, 16, v13
	v_and_b32_e32 v13, 0xffff0000, v13
	v_pk_add_f32 v[8:9], v[8:9], v[12:13]
	v_cvt_pk_bf16_f32 v12, v6, v7
	v_pk_mul_f32 v[6:7], v[6:7], v[6:7]
	v_cvt_pk_bf16_f32 v13, v8, v9
	v_pk_mul_f32 v[8:9], v[8:9], v[8:9]
	v_add_f32_e32 v5, v6, v7
	v_add_f32_e32 v5, v8, v5
	v_add_f32_e32 v5, v9, v5
	s_nop 1
	v_add_f32_dpp v5, v5, v5 quad_perm:[1,0,3,2] row_mask:0xf bank_mask:0xf
	global_store_dwordx2 v[10:11], v[12:13], off
	s_waitcnt lgkmcnt(0)
	s_nop 1
	v_add_f32_dpp v5, v5, v5 quad_perm:[2,3,0,1] row_mask:0xf bank_mask:0xf
	s_waitcnt lgkmcnt(0)
	s_nop 1
	v_add_f32_dpp v5, v5, v5 row_half_mirror row_mask:0xf bank_mask:0xf
	s_waitcnt lgkmcnt(0)
	s_nop 1
	v_add_f32_dpp v5, v5, v5 row_mirror row_mask:0xf bank_mask:0xf
	s_and_saveexec_b64 s[2:3], vcc
	s_cbranch_execz .LBB0_463
	v_lshlrev_b64 v[2:3], 6, v[2:3]
	v_lshl_add_u64 v[2:3], v[68:69], 0, v[2:3]
	s_waitcnt lgkmcnt(0)
	global_store_dword v[2:3], v5, off
.LBB0_463:
	s_or_b64 exec, exec, s[2:3]
	v_add_u32_e32 v2, 0x4c, v4
	v_ashrrev_i32_e32 v3, 31, v2
	v_lshlrev_b64 v[8:9], 11, v[2:3]
	v_lshl_add_u64 v[8:9], v[66:67], 0, v[8:9]
	s_waitcnt vmcnt(11)
	v_mov_b32_e32 v10, v236
	v_mov_b32_e32 v11, v237
	v_lshl_add_u64 v[232:233], v[8:9], 0, s[96:97]
	global_load_dwordx2 v[236:237], v[232:233], off
	s_waitcnt lgkmcnt(0)
	ds_read_b128 v[4:7], v72 offset:3264
	v_lshlrev_b32_e32 v12, 16, v10
	v_and_b32_e32 v13, 0xffff0000, v10
	s_waitcnt lgkmcnt(0)
	v_pk_add_f32 v[4:5], v[4:5], v[12:13]
	v_lshlrev_b32_e32 v10, 16, v11
	v_and_b32_e32 v11, 0xffff0000, v11
	v_pk_add_f32 v[6:7], v[6:7], v[10:11]
	v_cvt_pk_bf16_f32 v10, v4, v5
	v_pk_mul_f32 v[4:5], v[4:5], v[4:5]
	v_cvt_pk_bf16_f32 v11, v6, v7
	v_pk_mul_f32 v[6:7], v[6:7], v[6:7]
	v_add_f32_e32 v4, v4, v5
	v_add_f32_e32 v4, v6, v4
	v_add_f32_e32 v4, v7, v4
	s_nop 1
	v_add_f32_dpp v4, v4, v4 quad_perm:[1,0,3,2] row_mask:0xf bank_mask:0xf
	global_store_dwordx2 v[8:9], v[10:11], off
	s_waitcnt lgkmcnt(0)
	s_nop 1
	v_add_f32_dpp v4, v4, v4 quad_perm:[2,3,0,1] row_mask:0xf bank_mask:0xf
	s_waitcnt lgkmcnt(0)
	s_nop 1
	v_add_f32_dpp v4, v4, v4 row_half_mirror row_mask:0xf bank_mask:0xf
	s_waitcnt lgkmcnt(0)
	s_nop 1
	v_add_f32_dpp v4, v4, v4 row_mirror row_mask:0xf bank_mask:0xf
	s_and_saveexec_b64 s[2:3], vcc
	s_cbranch_execz .LBB0_456
	v_lshlrev_b64 v[2:3], 6, v[2:3]
	v_lshl_add_u64 v[2:3], v[68:69], 0, v[2:3]
	s_waitcnt lgkmcnt(0)
	global_store_dword v[2:3], v4, off
	s_branch .LBB0_456
